# attention P.V stage: constant parts of the 32 transposing V-read addresses moved into the DS offset field (32 fewer VALU per key tile per wave)
# speedup vs baseline: 1.0105x; 1.0105x over previous
; #define LAS __attribute__((address_space(3)))
; __device__ __forceinline__ float shx(float v, int mask, int lane) { return __int_as_float(__builtin_amdgcn_ds_bpermute((lane ^ mask) << 2, __float_as_int(v))); }
; __device__ __forceinline__ void attn_phase(int wv, PP P, int L, LAS unsigned char* lds) {
;     ...
;                 bf16x8 pf[2][2];
; #pragma unroll
;                 for (int m = 0; m < 2; ++m) {
;                     f32x4 sa[4];
; #pragma unroll
;                     for (int nt = 0; nt < 4; ++nt) { sa[nt] = (f32x4){0.f, 0.f, 0.f, 0.f};
; #pragma unroll
;                         for (int kk = 0; kk < 2; ++kk) { const bf16x8 kf = *(const LAS bf16x8*)(lds + kbuf + (nt * 16 + fr) * 272 + (m * 64 + kk * 32 + fq * 8) * 2);
;                             sa[nt] = __builtin_amdgcn_mfma_f32_16x16x32_bf16(kf, qf[m][kk], sa[nt], 0, 0, 0); } }
;                     float mx = -INFINITY;
; #pragma unroll
;                     for (int nt = 0; nt < 4; ++nt)
; #pragma unroll
;                         for (int q = 0; q < 4; ++q) { const bool kv = (kt > 0) || (nt * 16 + fq * 4 + q >= 48); sa[nt][q] = kv ? sa[nt][q] * 0.125f : -INFINITY; mx = fmaxf(mx, sa[nt][q]); }
;                     mx = fmaxf(mx, shx(mx, 16, lane)); mx = fmaxf(mx, shx(mx, 32, lane));
;                     const float mnew = fmaxf(mrun[m], mx); const float alpha = __expf(mrun[m] - mnew); mrun[m] = mnew;
;                     float rsum = 0.f;
; #pragma unroll
;                     for (int nt = 0; nt < 4; ++nt)
; #pragma unroll
;                         for (int q = 0; q < 4; ++q) { sa[nt][q] = __expf(sa[nt][q] - mnew); rsum += sa[nt][q]; }
;                     rsum += shx(rsum, 16, lane); rsum += shx(rsum, 32, lane);
;                     lrun[m] = lrun[m] * alpha + rsum;
.LBB0_373:
	v_add_u32_e32 v122, s7, v171
	ds_read_b128 v[92:95], v122
	ds_read_b128 v[98:101], v122 offset:64
	s_waitcnt lgkmcnt(1)
	v_mfma_f32_16x16x32_bf16 v[92:95], v[92:95], v[12:15], 0
	ds_read_b128 v[102:105], v122 offset:4416
	ds_read_b128 v[118:121], v122 offset:8768
	ds_read_b128 v[136:139], v122 offset:13120
	s_waitcnt lgkmcnt(3)
	v_mfma_f32_16x16x32_bf16 v[92:95], v[98:101], v[4:7], v[92:95]
	ds_read_b128 v[98:101], v122 offset:4352
	ds_read_b128 v[210:213], v122 offset:4544
	ds_read_b128 v[214:217], v122 offset:8896
	s_waitcnt lgkmcnt(2)
	v_mfma_f32_16x16x32_bf16 v[98:101], v[98:101], v[12:15], 0
	s_nop 2
	v_max3_f32 v97, v92, s52, v93
	v_mfma_f32_16x16x32_bf16 v[98:101], v[102:105], v[4:7], v[98:101]
	ds_read_b128 v[102:105], v122 offset:8704
	s_waitcnt lgkmcnt(0)
	v_mfma_f32_16x16x32_bf16 v[102:105], v[102:105], v[12:15], 0
	v_max3_f32 v97, v97, v94, v95
	s_nop 1
	v_mfma_f32_16x16x32_bf16 v[102:105], v[118:121], v[4:7], v[102:105]
	ds_read_b128 v[118:121], v122 offset:13056
	v_max3_f32 v97, v97, v98, v99
	s_waitcnt lgkmcnt(0)
	v_mfma_f32_16x16x32_bf16 v[118:121], v[118:121], v[12:15], 0
	v_max3_f32 v97, v97, v100, v101
	s_nop 0
	v_mfma_f32_16x16x32_bf16 v[160:163], v[136:139], v[4:7], v[118:121]
	s_nop 0
	v_max3_f32 v97, v97, v102, v103
	v_max3_f32 v97, v97, v104, v105
	s_nop 2
	s_nop 1
	v_max3_f32 v97, v97, v160, v161
	v_max3_f32 v97, v97, v162, v163
	v_mov_b32_e32 v106, v97
	s_nop 1
	v_permlane16_swap_b32_e32 v97, v106
	ds_read_b128 v[230:233], v122 offset:13248
	s_waitcnt lgkmcnt(1)
	v_max_f32_e32 v106, v106, v106
	v_max_f32_e32 v97, v97, v106
	v_mov_b32_e32 v106, v97
	s_nop 1
	v_permlane32_swap_b32_e32 v97, v106
	s_waitcnt lgkmcnt(0)
	v_max_f32_e32 v97, v97, v106
	v_mul_f32_e32 v97, s50, v97
	v_max_f32_e32 v131, v96, v97
	v_fma_f32 v92, v92, s50, -v131
	v_exp_f32_e32 v121, v92
	v_fma_f32 v92, v93, s50, -v131
	v_exp_f32_e32 v123, v92
	v_fma_f32 v92, v94, s50, -v131
	v_exp_f32_e32 v137, v92
	v_fma_f32 v92, v95, s50, -v131
	v_exp_f32_e32 v139, v92
	v_fma_f32 v92, v98, s50, -v131
	v_exp_f32_e32 v141, v92
	v_fma_f32 v92, v99, s50, -v131
	v_sub_f32_e32 v96, v96, v131
	v_exp_f32_e32 v143, v92
	v_fma_f32 v92, v100, s50, -v131
	v_exp_f32_e32 v145, v92
	v_fma_f32 v92, v101, s50, -v131
	v_exp_f32_e32 v116, v96
	v_exp_f32_e32 v147, v92
	v_fma_f32 v92, v102, s50, -v131
	v_exp_f32_e32 v149, v92
	v_fma_f32 v92, v103, s50, -v131
	v_pk_mul_f32 v[102:103], v[86:87], v[116:117] op_sel_hi:[1,0]
	v_pk_mul_f32 v[100:101], v[84:85], v[116:117] op_sel_hi:[1,0]
	v_pk_mul_f32 v[86:87], v[110:111], v[116:117] op_sel_hi:[1,0]
	v_pk_mul_f32 v[84:85], v[108:109], v[116:117] op_sel_hi:[1,0]
	ds_read_b128 v[108:111], v122 offset:128
	v_pk_mul_f32 v[98:99], v[82:83], v[116:117] op_sel_hi:[1,0]
	v_pk_mul_f32 v[96:97], v[80:81], v[116:117] op_sel_hi:[1,0]
	v_pk_mul_f32 v[82:83], v[114:115], v[116:117] op_sel_hi:[1,0]
	v_pk_mul_f32 v[80:81], v[112:113], v[116:117] op_sel_hi:[1,0]
	ds_read_b128 v[112:115], v122 offset:192
	s_waitcnt lgkmcnt(1)
	v_mfma_f32_16x16x32_bf16 v[108:111], v[108:111], v[8:11], 0
	v_exp_f32_e32 v151, v92
	v_fma_f32 v92, v104, s50, -v131
	s_waitcnt lgkmcnt(0)
	v_mfma_f32_16x16x32_bf16 v[108:111], v[112:115], v[16:19], v[108:111]
	ds_read_b128 v[112:115], v122 offset:4480
	v_exp_f32_e32 v153, v92
	s_waitcnt lgkmcnt(0)
	v_mfma_f32_16x16x32_bf16 v[112:115], v[112:115], v[8:11], 0
	s_nop 2
	s_nop 0
	v_max3_f32 v118, v108, s52, v109
	v_mfma_f32_16x16x32_bf16 v[112:115], v[210:213], v[16:19], v[112:115]
	ds_read_b128 v[210:213], v122 offset:8832
	s_waitcnt lgkmcnt(0)
	v_mfma_f32_16x16x32_bf16 v[210:213], v[210:213], v[8:11], 0
	v_max3_f32 v118, v118, v110, v111
	s_nop 1
	v_mfma_f32_16x16x32_bf16 v[210:213], v[214:217], v[16:19], v[210:213]
	ds_read_b128 v[214:217], v122 offset:13184
	v_max3_f32 v118, v118, v112, v113
	s_waitcnt lgkmcnt(0)
	v_mfma_f32_16x16x32_bf16 v[214:217], v[214:217], v[8:11], 0
	v_max3_f32 v118, v118, v114, v115
	s_nop 0
	v_mfma_f32_16x16x32_bf16 v[214:217], v[230:233], v[16:19], v[214:217]
	s_nop 0
	v_max3_f32 v118, v118, v210, v211
	v_max3_f32 v118, v118, v212, v213
	s_nop 2
	s_nop 1
	v_max3_f32 v118, v118, v214, v215
	v_max3_f32 v118, v118, v216, v217
	v_mov_b32_e32 v119, v118
	s_nop 1
	v_permlane16_swap_b32_e32 v118, v119
	v_fma_f32 v92, v105, s50, -v131
	v_exp_f32_e32 v155, v92
	v_fma_f32 v92, v160, s50, -v131
	s_waitcnt lgkmcnt(0)
	v_max_f32_e32 v119, v119, v119
	v_max_f32_e32 v118, v118, v119
	v_mov_b32_e32 v119, v118
	s_nop 1
	v_permlane32_swap_b32_e32 v118, v119
	v_exp_f32_e32 v157, v92
	v_fma_f32 v92, v161, s50, -v131
	s_waitcnt lgkmcnt(0)
; __device__ __forceinline__ float shx(float v, int mask, int lane) { return __int_as_float(__builtin_amdgcn_ds_bpermute((lane ^ mask) << 2, __float_as_int(v))); }
; __device__ __forceinline__ u32x2 trr(unsigned addr) { u32x2 r; asm volatile("ds_read_b64_tr_b16 %0, %1" : "=&v"(r) : "v"(addr) : "memory"); return r; }
; __device__ __forceinline__ unsigned pack2(float lo, float hi) { unsigned r; asm("v_cvt_pk_bf16_f32 %0, %1, %2" : "=v"(r) : "v"(lo), "v"(hi)); return r; }
; __device__ __forceinline__ void attn_phase(int wv, PP P, int L, LAS unsigned char* lds) {
;     ...
;                     const float mnew = fmaxf(mrun[m], mx); const float alpha = __expf(mrun[m] - mnew); mrun[m] = mnew;
;                     float rsum = 0.f;
; #pragma unroll
;                     for (int nt = 0; nt < 4; ++nt)
; #pragma unroll
;                         for (int q = 0; q < 4; ++q) { sa[nt][q] = __expf(sa[nt][q] - mnew); rsum += sa[nt][q]; }
;                     rsum += shx(rsum, 16, lane); rsum += shx(rsum, 32, lane);
;                     lrun[m] = lrun[m] * alpha + rsum;
; #pragma unroll
;                     for (int e = 0; e < 8; ++e) O[m][e] *= alpha;
; #pragma unroll
;                     for (int kp = 0; kp < 2; ++kp) { u32x4 t; t.x = pack2(sa[2 * kp][0], sa[2 * kp][1]); t.y = pack2(sa[2 * kp][2], sa[2 * kp][3]); t.z = pack2(sa[2 * kp + 1][0], sa[2 * kp + 1][1]); t.w = pack2(sa[2 * kp + 1][2], sa[2 * kp + 1][3]);
;                         pf[m][kp] = __builtin_bit_cast(bf16x8, t); }
;                 }
;                 const unsigned trv = ldsb + vbuf + (4 * fq + trq) * 272 + (4 * trp) * 2;
; #pragma unroll
;                 for (int kp = 0; kp < 2; ++kp) {
;                     u32x2 vl[8], vh[8];
; #pragma unroll
;                     for (int e = 0; e < 8; ++e) { vl[e] = trr(trv + (32 * kp) * 272 + e * 32); vh[e] = trr(trv + (32 * kp + 16) * 272 + e * 32); }
	v_max_f32_e32 v118, v118, v119
	v_mul_f32_e32 v118, s50, v118
	v_max_f32_e32 v209, v117, v118
	v_fma_f32 v108, v108, s50, -v209
	v_exp_f32_e32 v120, v108
	v_fma_f32 v108, v109, s50, -v209
	v_exp_f32_e32 v122, v108
	v_fma_f32 v108, v110, s50, -v209
	v_exp_f32_e32 v136, v108
	v_fma_f32 v108, v111, s50, -v209
	v_exp_f32_e32 v138, v108
	v_fma_f32 v108, v112, s50, -v209
	v_exp_f32_e32 v140, v108
	v_fma_f32 v108, v113, s50, -v209
	v_exp_f32_e32 v142, v108
	v_fma_f32 v108, v114, s50, -v209
	v_exp_f32_e32 v144, v108
	v_fma_f32 v108, v115, s50, -v209
	v_fma_f32 v110, v211, s50, -v209
	v_exp_f32_e32 v146, v108
	v_fma_f32 v108, v210, s50, -v209
	v_exp_f32_e32 v150, v110
	v_fma_f32 v110, v212, s50, -v209
	v_exp_f32_e32 v148, v108
	v_pk_add_f32 v[108:109], v[120:121], 0 op_sel_hi:[1,0]
	v_pk_add_f32 v[108:109], v[122:123], v[108:109]
	v_exp_f32_e32 v152, v110
	v_fma_f32 v110, v213, s50, -v209
	v_pk_add_f32 v[108:109], v[136:137], v[108:109]
	v_pk_add_f32 v[108:109], v[138:139], v[108:109]
	v_exp_f32_e32 v154, v110
	v_fma_f32 v110, v214, s50, -v209
	v_pk_add_f32 v[108:109], v[140:141], v[108:109]
	v_pk_add_f32 v[108:109], v[142:143], v[108:109]
	v_exp_f32_e32 v156, v110
	v_fma_f32 v110, v215, s50, -v209
	v_pk_add_f32 v[108:109], v[144:145], v[108:109]
	v_exp_f32_e32 v159, v92
	v_fma_f32 v92, v162, s50, -v131
	v_pk_add_f32 v[108:109], v[146:147], v[108:109]
	v_exp_f32_e32 v158, v110
	v_fma_f32 v110, v216, s50, -v209
	v_pk_add_f32 v[108:109], v[148:149], v[108:109]
	v_exp_f32_e32 v161, v92
	v_fma_f32 v92, v163, s50, -v131
	v_exp_f32_e32 v160, v110
	v_fma_f32 v110, v217, s50, -v209
	v_pk_add_f32 v[108:109], v[150:151], v[108:109]
	v_pk_add_f32 v[108:109], v[152:153], v[108:109]
	v_exp_f32_e32 v163, v92
	v_exp_f32_e32 v162, v110
	v_pk_add_f32 v[108:109], v[154:155], v[108:109]
	v_pk_mul_f32 v[106:107], v[74:75], v[116:117] op_sel_hi:[1,0]
	v_pk_add_f32 v[108:109], v[156:157], v[108:109]
	v_pk_mul_f32 v[104:105], v[72:73], v[116:117] op_sel_hi:[1,0]
	v_pk_add_f32 v[108:109], v[158:159], v[108:109]
	v_pk_mul_f32 v[94:95], v[78:79], v[116:117] op_sel_hi:[1,0]
	v_pk_add_f32 v[108:109], v[160:161], v[108:109]
	v_pk_mul_f32 v[92:93], v[76:77], v[116:117] op_sel_hi:[1,0]
	v_pk_add_f32 v[108:109], v[162:163], v[108:109]
	v_mov_b32_e32 v111, v109
	v_mov_b32_e32 v110, v108
	s_nop 0
	v_permlane16_swap_b32_e32 v109, v111
	v_permlane16_swap_b32_e32 v108, v110
	v_pk_mul_f32 v[90:91], v[90:91], v[116:117] op_sel_hi:[1,0]
	v_pk_mul_f32 v[88:89], v[88:89], v[116:117] op_sel_hi:[1,0]
	v_pk_mul_f32 v[74:75], v[70:71], v[116:117] op_sel_hi:[1,0]
	v_pk_mul_f32 v[72:73], v[68:69], v[116:117] op_sel_hi:[1,0]
	s_waitcnt lgkmcnt(0)
	v_pk_add_f32 v[108:109], v[108:109], v[110:111]
	v_sub_f32_e32 v117, v117, v209
	v_mov_b32_e32 v111, v109
	v_mov_b32_e32 v110, v108
	s_nop 0
	v_permlane32_swap_b32_e32 v109, v111
	v_permlane32_swap_b32_e32 v108, v110
	v_exp_f32_e32 v214, v117
	v_mov_b32_e32 v215, v116
	v_add_u32_e32 v216, s7, v167
	s_waitcnt lgkmcnt(0)
	v_pk_add_f32 v[108:109], v[108:109], v[110:111]
	v_pk_mul_f32 v[116:117], v[40:41], v[214:215] op_sel_hi:[1,0]
	v_pk_fma_f32 v[134:135], v[134:135], v[214:215], v[108:109]
	v_pk_mul_f32 v[108:109], v[44:45], v[214:215] op_sel_hi:[1,0]
	v_pk_mul_f32 v[44:45], v[56:57], v[214:215] op_sel_hi:[1,0]
	v_pk_mul_f32 v[40:41], v[60:61], v[214:215] op_sel_hi:[1,0]
	ds_read_b64_tr_b16 v[60:61], v216 offset:34816
	v_pk_mul_f32 v[118:119], v[42:43], v[214:215] op_sel_hi:[1,0]
	v_pk_mul_f32 v[42:43], v[62:63], v[214:215] op_sel_hi:[1,0]
	ds_read_b64_tr_b16 v[62:63], v216 offset:39168
	v_cvt_pk_bf16_f32 v77, v137, v139
	v_pk_mul_f32 v[210:211], v[48:49], v[214:215] op_sel_hi:[1,0]
	v_pk_mul_f32 v[48:49], v[52:53], v[214:215] op_sel_hi:[1,0]
	v_cvt_pk_bf16_f32 v53, v136, v138
	ds_read_b64_tr_b16 v[136:137], v216 offset:34848
	ds_read_b64_tr_b16 v[138:139], v216 offset:39200
	v_cvt_pk_bf16_f32 v78, v141, v143
	v_pk_mul_f32 v[212:213], v[50:51], v[214:215] op_sel_hi:[1,0]
	v_pk_mul_f32 v[50:51], v[54:55], v[214:215] op_sel_hi:[1,0]
	v_cvt_pk_bf16_f32 v54, v140, v142
	ds_read_b64_tr_b16 v[140:141], v216 offset:34880
	ds_read_b64_tr_b16 v[142:143], v216 offset:39232
	v_cvt_pk_bf16_f32 v79, v145, v147
	v_cvt_pk_bf16_f32 v55, v144, v146
	ds_read_b64_tr_b16 v[144:145], v216 offset:34912
	ds_read_b64_tr_b16 v[146:147], v216 offset:39264
	v_cvt_pk_bf16_f32 v68, v149, v151
	v_pk_mul_f32 v[112:113], v[36:37], v[214:215] op_sel_hi:[1,0]
	v_pk_mul_f32 v[36:37], v[64:65], v[214:215] op_sel_hi:[1,0]
	v_cvt_pk_bf16_f32 v64, v148, v150
	ds_read_b64_tr_b16 v[148:149], v216 offset:34944
	ds_read_b64_tr_b16 v[150:151], v216 offset:39296
	v_cvt_pk_bf16_f32 v69, v153, v155
	v_cvt_pk_bf16_f32 v65, v152, v154
	ds_read_b64_tr_b16 v[152:153], v216 offset:34976
	ds_read_b64_tr_b16 v[154:155], v216 offset:39328
	v_cvt_pk_bf16_f32 v70, v157, v159
	v_pk_mul_f32 v[114:115], v[38:39], v[214:215] op_sel_hi:[1,0]
	v_pk_mul_f32 v[38:39], v[66:67], v[214:215] op_sel_hi:[1,0]
	v_cvt_pk_bf16_f32 v66, v156, v158
	ds_read_b64_tr_b16 v[156:157], v216 offset:35008
	ds_read_b64_tr_b16 v[158:159], v216 offset:39360
	v_cvt_pk_bf16_f32 v76, v121, v123
	v_cvt_pk_bf16_f32 v52, v120, v122
	ds_read_b64_tr_b16 v[120:121], v216 offset:35040
	ds_read_b64_tr_b16 v[122:123], v216 offset:39392
	s_waitcnt lgkmcnt(0)
; __device__ __forceinline__ u32x2 trr(unsigned addr) { u32x2 r; asm volatile("ds_read_b64_tr_b16 %0, %1" : "=&v"(r) : "v"(addr) : "memory"); return r; }
; __device__ __forceinline__ void trw4(u32x2& a, u32x2& b, u32x2& c, u32x2& d) { asm volatile("s_waitcnt lgkmcnt(0)" : "+v"(a), "+v"(b), "+v"(c), "+v"(d) : : "memory"); }
; __device__ __forceinline__ void attn_phase(int wv, PP P, int L, LAS unsigned char* lds) {
;     ...
;                 const unsigned trv = ldsb + vbuf + (4 * fq + trq) * 272 + (4 * trp) * 2;
; #pragma unroll
;                 for (int kp = 0; kp < 2; ++kp) {
;                     u32x2 vl[8], vh[8];
; #pragma unroll
;                     for (int e = 0; e < 8; ++e) { vl[e] = trr(trv + (32 * kp) * 272 + e * 32); vh[e] = trr(trv + (32 * kp + 16) * 272 + e * 32); }
;                     trw4(vl[0], vl[1], vl[2], vl[3]); trw4(vl[4], vl[5], vl[6], vl[7]); trw4(vh[0], vh[1], vh[2], vh[3]); trw4(vh[4], vh[5], vh[6], vh[7]);
; #pragma unroll
;                     for (int e = 0; e < 8; ++e) { const bf16x8 vf = mk8(vl[e], vh[e]);
;                         O[0][e] = __builtin_amdgcn_mfma_f32_16x16x32_bf16(vf, pf[0][kp], O[0][e], 0, 0, 0);
;                         O[1][e] = __builtin_amdgcn_mfma_f32_16x16x32_bf16(vf, pf[1][kp], O[1][e], 0, 0, 0); }
;                 }
	s_waitcnt lgkmcnt(0)
	s_waitcnt lgkmcnt(0)
	v_pk_mul_f32 v[110:111], v[46:47], v[214:215] op_sel_hi:[1,0]
	v_pk_mul_f32 v[46:47], v[58:59], v[214:215] op_sel_hi:[1,0]
	s_waitcnt lgkmcnt(0)
	v_mfma_f32_16x16x32_bf16 v[56:59], v[60:63], v[76:79], v[104:107]
	v_cvt_pk_bf16_f32 v71, v161, v163
	v_cvt_pk_bf16_f32 v67, v160, v162
	v_mfma_f32_16x16x32_bf16 v[100:103], v[136:139], v[76:79], v[100:103]
	v_mfma_f32_16x16x32_bf16 v[104:107], v[136:139], v[52:55], v[116:119]
	v_mfma_f32_16x16x32_bf16 v[96:99], v[140:143], v[76:79], v[96:99]
	v_mfma_f32_16x16x32_bf16 v[112:115], v[140:143], v[52:55], v[112:115]
	v_mfma_f32_16x16x32_bf16 v[136:139], v[152:155], v[76:79], v[84:87]
	v_mfma_f32_16x16x32_bf16 v[140:143], v[152:155], v[52:55], v[44:47]
	v_mfma_f32_16x16x32_bf16 v[152:155], v[120:123], v[76:79], v[72:75]
	s_nop 1
	v_mfma_f32_16x16x32_bf16 v[120:123], v[120:123], v[52:55], v[36:39]
	s_nop 2
	ds_read_b64_tr_b16 v[36:37], v216 offset:43520
	v_mfma_f32_16x16x32_bf16 v[88:91], v[148:151], v[76:79], v[88:91]
	v_mfma_f32_16x16x32_bf16 v[116:119], v[148:151], v[52:55], v[48:51]
	v_mfma_f32_16x16x32_bf16 v[148:151], v[156:159], v[52:55], v[40:43]
	s_nop 1
	ds_read_b64_tr_b16 v[38:39], v216 offset:47872
	ds_read_b64_tr_b16 v[40:41], v216 offset:43552
	ds_read_b64_tr_b16 v[42:43], v216 offset:47904
	ds_read_b64_tr_b16 v[44:45], v216 offset:43584
	ds_read_b64_tr_b16 v[46:47], v216 offset:47936
	v_mfma_f32_16x16x32_bf16 v[60:63], v[60:63], v[52:55], v[210:213]
	v_mfma_f32_16x16x32_bf16 v[108:111], v[144:147], v[52:55], v[108:111]
	ds_read_b64_tr_b16 v[52:53], v216 offset:43616
	ds_read_b64_tr_b16 v[54:55], v216 offset:47968
	v_mfma_f32_16x16x32_bf16 v[92:95], v[144:147], v[76:79], v[92:95]
	v_mfma_f32_16x16x32_bf16 v[144:147], v[156:159], v[76:79], v[80:83]
	ds_read_b64_tr_b16 v[156:157], v216 offset:43648
	ds_read_b64_tr_b16 v[158:159], v216 offset:48000
	ds_read_b64_tr_b16 v[160:161], v216 offset:43680
	ds_read_b64_tr_b16 v[162:163], v216 offset:48032
	ds_read_b64_tr_b16 v[210:211], v216 offset:43712
	ds_read_b64_tr_b16 v[212:213], v216 offset:48064
	ds_read_b64_tr_b16 v[214:215], v216 offset:43744
	ds_read_b64_tr_b16 v[216:217], v216 offset:48096
	s_waitcnt lgkmcnt(0)
	s_waitcnt lgkmcnt(0)
	s_waitcnt lgkmcnt(0)
	s_nop 0
	s_waitcnt lgkmcnt(0)
	v_mfma_f32_16x16x32_bf16 v[72:75], v[36:39], v[68:71], v[56:59]
	v_mfma_f32_16x16x32_bf16 v[48:51], v[36:39], v[64:67], v[60:63]
	v_mfma_f32_16x16x32_bf16 v[84:87], v[40:43], v[68:71], v[100:103]
	v_mfma_f32_16x16x32_bf16 v[40:43], v[40:43], v[64:67], v[104:107]
	v_mfma_f32_16x16x32_bf16 v[80:83], v[44:47], v[68:71], v[96:99]
	v_mfma_f32_16x16x32_bf16 v[36:39], v[44:47], v[64:67], v[112:115]
	s_nop 1
	v_mov_b32_e32 v96, v131
	v_mfma_f32_16x16x32_bf16 v[76:79], v[52:55], v[68:71], v[92:95]
	v_mfma_f32_16x16x32_bf16 v[44:47], v[52:55], v[64:67], v[108:111]
	v_mfma_f32_16x16x32_bf16 v[88:91], v[156:159], v[68:71], v[88:91]
	v_mfma_f32_16x16x32_bf16 v[52:55], v[156:159], v[64:67], v[116:119]
	v_mfma_f32_16x16x32_bf16 v[108:111], v[160:163], v[68:71], v[136:139]
	s_nop 1
	v_mov_b32_e32 v117, v209
	v_mfma_f32_16x16x32_bf16 v[56:59], v[160:163], v[64:67], v[140:143]
	v_mfma_f32_16x16x32_bf16 v[112:115], v[210:213], v[68:71], v[144:147]
	v_mfma_f32_16x16x32_bf16 v[60:63], v[210:213], v[64:67], v[148:151]
	v_mfma_f32_16x16x32_bf16 v[68:71], v[214:217], v[68:71], v[152:155]
	v_mfma_f32_16x16x32_bf16 v[64:67], v[214:217], v[64:67], v[120:123]
	s_cmp_eq_u32 s24, s6
	s_cbranch_scc1 .LBB0_375
